# v52 + V pieces issued before K pieces inside each tile's LDS-DMA batch
# speedup vs baseline: 1.0313x; 1.0313x over previous
; #define SBAR() __builtin_amdgcn_sched_barrier(0)
; #define ATT_DMA_K(t) do { const bf16_t* kg_ = Kh + (size_t)(t) * 64 * LDK; LAS unsigned char* sb_ = lds + ((t) & 3) * KBUF; \
;     _Pragma("unroll") for (int i_ = 0; i_ < NKP; ++i_) __builtin_amdgcn_global_load_lds((const unsigned*)(kg_ + kgo[i_]), (LAS unsigned*)(sb_ + (wid + 8 * i_) * 1024), 16, 0, 0); } while (0)
; #define ATT_DMA_V(t, vs) do { const bf16_t* vg_ = Vh + (size_t)(t) * 64 * LDV; LAS unsigned char* sb_ = lds + V_OFF + (vs) * SHM_V; \
;     _Pragma("unroll") for (int i_ = 0; i_ < 2; ++i_) __builtin_amdgcn_global_load_lds((const unsigned*)(vg_ + vgo[i_]), (LAS unsigned*)(sb_ + (2 * wid + i_) * 1024), 16, 0, 0); } while (0)
; #define ATT_SEG(t) do { if constexpr (MODE != 0) { if (((t) == tL && tL > 0) || (t) == tR) { const float f_ = (t) == tR ? fR : fL; l_reg *= f_; \
;     _Pragma("unroll") for (int d = 0; d < 4; ++d) _Pragma("unroll") for (int r = 0; r < 16; ++r) o[d][r] *= f_; } } } while (0)
; #define ATT_TOP(N) do { asm volatile("s_waitcnt vmcnt(%0)" :: "n"(N) : "memory"); __builtin_amdgcn_s_barrier(); asm volatile("" ::: "memory"); } while (0)
; template <int DQK, int MODE, int LDQ, int LDK, int LDV> ...
;     ...
;     for (int j = 0; j < NT; ++j) {
;         if (j + 2 < NT) ATT_TOP(NKP + 2); else ATT_TOP(0);
;         if (j + 3 < NT) ATT_DMA_K(j + 3);
;         if (j + 2 < NT) ATT_DMA_V(j + 2, v2);
;         ATT_SEG(j); SBAR();
.Lstg_d0_top_10:
	s_setprio 0
	s_add_i32 s1, s95, s1
	s_mov_b32 m0, s1
	s_add_i32 s2, s1, 0x400
	global_load_lds_dwordx4 v[102:103], off
	s_mov_b32 m0, s2
	s_add_i32 s1, s62, s0
	global_load_lds_dwordx4 v[104:105], off
	s_mov_b32 m0, s98
	s_add_i32 s74, s6, s0
	global_load_lds_dwordx4 v[100:101], off
	s_cmp_eq_u32 s1, 1
	s_cselect_b64 s[2:3], -1, 0
	s_and_b64 vcc, s[4:5], s[2:3]
	s_cmp_eq_u32 s74, 1
	s_cselect_b64 s[2:3], -1, 0
	s_or_b64 vcc, s[2:3], vcc
	s_andn2_b64 vcc, exec, vcc
	s_mov_b32 s1, s23
	s_cbranch_vccnz .LBB0_1922
	v_cndmask_b32_e64 v122, v112, v113, s[2:3]
	v_pk_mul_f32 v[14:15], v[14:15], v[122:123] op_sel_hi:[1,0]
	v_pk_mul_f32 v[12:13], v[12:13], v[122:123] op_sel_hi:[1,0]
	v_pk_mul_f32 v[10:11], v[10:11], v[122:123] op_sel_hi:[1,0]
	v_pk_mul_f32 v[8:9], v[8:9], v[122:123] op_sel_hi:[1,0]
	v_pk_mul_f32 v[6:7], v[6:7], v[122:123] op_sel_hi:[1,0]
	v_pk_mul_f32 v[4:5], v[4:5], v[122:123] op_sel_hi:[1,0]
	v_pk_mul_f32 v[2:3], v[2:3], v[122:123] op_sel_hi:[1,0]
	v_pk_mul_f32 v[0:1], v[0:1], v[122:123] op_sel_hi:[1,0]
	v_pk_mul_f32 v[62:63], v[62:63], v[122:123] op_sel_hi:[1,0]
	v_pk_mul_f32 v[60:61], v[60:61], v[122:123] op_sel_hi:[1,0]
	v_pk_mul_f32 v[58:59], v[58:59], v[122:123] op_sel_hi:[1,0]
	v_pk_mul_f32 v[56:57], v[56:57], v[122:123] op_sel_hi:[1,0]
	v_pk_mul_f32 v[54:55], v[54:55], v[122:123] op_sel_hi:[1,0]
	v_pk_mul_f32 v[52:53], v[52:53], v[122:123] op_sel_hi:[1,0]
	v_pk_mul_f32 v[50:51], v[50:51], v[122:123] op_sel_hi:[1,0]
	v_pk_mul_f32 v[48:49], v[48:49], v[122:123] op_sel_hi:[1,0]
	v_pk_mul_f32 v[46:47], v[46:47], v[122:123] op_sel_hi:[1,0]
	v_pk_mul_f32 v[44:45], v[44:45], v[122:123] op_sel_hi:[1,0]
	v_pk_mul_f32 v[42:43], v[42:43], v[122:123] op_sel_hi:[1,0]
	v_pk_mul_f32 v[40:41], v[40:41], v[122:123] op_sel_hi:[1,0]
	v_pk_mul_f32 v[38:39], v[38:39], v[122:123] op_sel_hi:[1,0]
	v_pk_mul_f32 v[36:37], v[36:37], v[122:123] op_sel_hi:[1,0]
	v_pk_mul_f32 v[34:35], v[34:35], v[122:123] op_sel_hi:[1,0]
	v_pk_mul_f32 v[32:33], v[32:33], v[122:123] op_sel_hi:[1,0]
	v_pk_mul_f32 v[30:31], v[30:31], v[122:123] op_sel_hi:[1,0]
	v_pk_mul_f32 v[28:29], v[28:29], v[122:123] op_sel_hi:[1,0]
	v_pk_mul_f32 v[26:27], v[26:27], v[122:123] op_sel_hi:[1,0]
	v_pk_mul_f32 v[24:25], v[24:25], v[122:123] op_sel_hi:[1,0]
	v_pk_mul_f32 v[22:23], v[22:23], v[122:123] op_sel_hi:[1,0]
	v_pk_mul_f32 v[20:21], v[20:21], v[122:123] op_sel_hi:[1,0]
	v_pk_mul_f32 v[18:19], v[18:19], v[122:123] op_sel_hi:[1,0]
	v_pk_mul_f32 v[16:17], v[16:17], v[122:123] op_sel_hi:[1,0]
	v_mul_f32_e32 v120, v120, v122

; #define SBAR() __builtin_amdgcn_sched_barrier(0)
; #define ATT_DMA_K(t) do { const bf16_t* kg_ = Kh + (size_t)(t) * 64 * LDK; LAS unsigned char* sb_ = lds + ((t) & 3) * KBUF; \
;     _Pragma("unroll") for (int i_ = 0; i_ < NKP; ++i_) __builtin_amdgcn_global_load_lds((const unsigned*)(kg_ + kgo[i_]), (LAS unsigned*)(sb_ + (wid + 8 * i_) * 1024), 16, 0, 0); } while (0)
; #define ATT_DMA_V(t, vs) do { const bf16_t* vg_ = Vh + (size_t)(t) * 64 * LDV; LAS unsigned char* sb_ = lds + V_OFF + (vs) * SHM_V; \
;     _Pragma("unroll") for (int i_ = 0; i_ < 2; ++i_) __builtin_amdgcn_global_load_lds((const unsigned*)(vg_ + vgo[i_]), (LAS unsigned*)(sb_ + (2 * wid + i_) * 1024), 16, 0, 0); } while (0)
; #define ATT_SEG(t) do { if constexpr (MODE != 0) { if (((t) == tL && tL > 0) || (t) == tR) { const float f_ = (t) == tR ? fR : fL; l_reg *= f_; \
;     _Pragma("unroll") for (int d = 0; d < 4; ++d) _Pragma("unroll") for (int r = 0; r < 16; ++r) o[d][r] *= f_; } } } while (0)
; #define ATT_TOP(N) do { asm volatile("s_waitcnt vmcnt(%0)" :: "n"(N) : "memory"); __builtin_amdgcn_s_barrier(); asm volatile("" ::: "memory"); } while (0)
; template <int DQK, int MODE, int LDQ, int LDK, int LDV> ...
;     ...
;     for (int j = 0; j < NT; ++j) {
;         if (j + 2 < NT) ATT_TOP(NKP + 2); else ATT_TOP(0);
;         if (j + 3 < NT) ATT_DMA_K(j + 3);
;         if (j + 2 < NT) ATT_DMA_V(j + 2, v2);
;         ATT_SEG(j); SBAR();
.Lstg_d1_top_18:
	s_setprio 0
	s_add_i32 s2, s48, s2
	s_mov_b32 m0, s2
	s_add_i32 s3, s2, 0x400
	global_load_lds_dwordx4 v[102:103], off
	s_mov_b32 m0, s3
	s_add_i32 s2, s53, s0
	global_load_lds_dwordx4 v[104:105], off
	s_mov_b32 m0, s98
	s_add_i32 s23, s6, s0
	global_load_lds_dwordx4 v[100:101], off
	s_cmp_eq_u32 s2, 1
	s_cselect_b64 s[2:3], -1, 0
	s_and_b64 s[74:75], s[4:5], s[2:3]
	s_cmp_eq_u32 s23, 1
	s_cselect_b64 s[2:3], -1, 0
	s_or_b64 s[74:75], s[2:3], s[74:75]
	s_andn2_b64 vcc, exec, s[74:75]
	s_mov_b32 s23, s62
	s_cbranch_vccnz .LBB0_1953
	v_cndmask_b32_e64 v122, v112, v113, s[2:3]
	v_pk_mul_f32 v[14:15], v[14:15], v[122:123] op_sel_hi:[1,0]
	v_pk_mul_f32 v[12:13], v[12:13], v[122:123] op_sel_hi:[1,0]
	v_pk_mul_f32 v[10:11], v[10:11], v[122:123] op_sel_hi:[1,0]
	v_pk_mul_f32 v[8:9], v[8:9], v[122:123] op_sel_hi:[1,0]
	v_pk_mul_f32 v[6:7], v[6:7], v[122:123] op_sel_hi:[1,0]
	v_pk_mul_f32 v[4:5], v[4:5], v[122:123] op_sel_hi:[1,0]
	v_pk_mul_f32 v[2:3], v[2:3], v[122:123] op_sel_hi:[1,0]
	v_pk_mul_f32 v[0:1], v[0:1], v[122:123] op_sel_hi:[1,0]
	v_pk_mul_f32 v[62:63], v[62:63], v[122:123] op_sel_hi:[1,0]
	v_pk_mul_f32 v[60:61], v[60:61], v[122:123] op_sel_hi:[1,0]
	v_pk_mul_f32 v[58:59], v[58:59], v[122:123] op_sel_hi:[1,0]
	v_pk_mul_f32 v[56:57], v[56:57], v[122:123] op_sel_hi:[1,0]
	v_pk_mul_f32 v[54:55], v[54:55], v[122:123] op_sel_hi:[1,0]
	v_pk_mul_f32 v[52:53], v[52:53], v[122:123] op_sel_hi:[1,0]
	v_pk_mul_f32 v[50:51], v[50:51], v[122:123] op_sel_hi:[1,0]
	v_pk_mul_f32 v[48:49], v[48:49], v[122:123] op_sel_hi:[1,0]
	v_pk_mul_f32 v[30:31], v[30:31], v[122:123] op_sel_hi:[1,0]
	v_pk_mul_f32 v[28:29], v[28:29], v[122:123] op_sel_hi:[1,0]
	v_pk_mul_f32 v[26:27], v[26:27], v[122:123] op_sel_hi:[1,0]
	v_pk_mul_f32 v[24:25], v[24:25], v[122:123] op_sel_hi:[1,0]
	v_pk_mul_f32 v[22:23], v[22:23], v[122:123] op_sel_hi:[1,0]
	v_pk_mul_f32 v[20:21], v[20:21], v[122:123] op_sel_hi:[1,0]
	v_pk_mul_f32 v[18:19], v[18:19], v[122:123] op_sel_hi:[1,0]
	v_pk_mul_f32 v[16:17], v[16:17], v[122:123] op_sel_hi:[1,0]
	v_pk_mul_f32 v[46:47], v[46:47], v[122:123] op_sel_hi:[1,0]
	v_pk_mul_f32 v[44:45], v[44:45], v[122:123] op_sel_hi:[1,0]
	v_pk_mul_f32 v[42:43], v[42:43], v[122:123] op_sel_hi:[1,0]
	v_pk_mul_f32 v[40:41], v[40:41], v[122:123] op_sel_hi:[1,0]
	v_pk_mul_f32 v[38:39], v[38:39], v[122:123] op_sel_hi:[1,0]
	v_pk_mul_f32 v[36:37], v[36:37], v[122:123] op_sel_hi:[1,0]
	v_pk_mul_f32 v[34:35], v[34:35], v[122:123] op_sel_hi:[1,0]
	v_pk_mul_f32 v[32:33], v[32:33], v[122:123] op_sel_hi:[1,0]
	v_mul_f32_e32 v120, v120, v122

.Lstg_mla_top_2:
	s_setprio 0
	s_mov_b32 s0, s5
	s_mov_b32 s5, s44
	s_mov_b32 s44, s4
	s_lshl_b32 s4, s4, 14
	s_add_i32 s4, s52, s4
	s_mov_b32 m0, s4
	s_add_i32 s6, s4, 0x400
	global_load_lds_dwordx4 v144, s[34:35]
	s_mov_b32 m0, s6
	s_nop 0
	global_load_lds_dwordx4 v142, s[34:35]
	s_mov_b32 m0, s1
	s_nop 0
	global_load_lds_dwordx4 v136, s[34:35]
	s_add_i32 m0, s1, 0x2000
	s_nop 0
	global_load_lds_dwordx4 v138, s[34:35]
	s_add_i32 m0, s1, 0x4000
	s_add_i32 s1, s43, -3
	global_load_lds_dwordx4 v140, s[34:35]
	s_and_b32 s1, s1, 3
	s_mulk_i32 s1, 0x6000
	v_add_u32_e32 v246, s1, v158
	v_add_u32_e32 v174, v246, v151
	v_add_u32_e32 v178, v246, v149
	v_add_u32_e32 v182, v246, v148
	v_add_u32_e32 v186, v246, v147
	s_lshl_b32 s1, s0, 14
	ds_read_b128 v[190:193], v174 offset:12416
	ds_read_b128 v[194:197], v178 offset:12416
	ds_read_b128 v[174:177], v174 offset:12288
	ds_read_b128 v[178:181], v178 offset:12288
	ds_read_b128 v[182:185], v182 offset:12288
	ds_read_b128 v[186:189], v186 offset:12288
	v_add_u32_e32 v254, s1, v130
	ds_read_b64_tr_b16 v[198:199], v254 offset:0
	ds_read_b64_tr_b16 v[200:201], v254 offset:0x800
	ds_read_b64_tr_b16 v[202:203], v254 offset:0x1000
	ds_read_b64_tr_b16 v[204:205], v254 offset:0x1800
	ds_read_b64_tr_b16 v[206:207], v254 offset:0x200
	ds_read_b64_tr_b16 v[208:209], v254 offset:0xa00
	ds_read_b64_tr_b16 v[210:211], v254 offset:0x1200
	ds_read_b64_tr_b16 v[212:213], v254 offset:0x1a00
	ds_read_b64_tr_b16 v[214:215], v254 offset:0x400
	ds_read_b64_tr_b16 v[216:217], v254 offset:0xc00
	ds_read_b64_tr_b16 v[218:219], v254 offset:0x1400
	ds_read_b64_tr_b16 v[220:221], v254 offset:0x1c00
	ds_read_b64_tr_b16 v[222:223], v254 offset:0x600
	ds_read_b64_tr_b16 v[224:225], v254 offset:0xe00
	ds_read_b64_tr_b16 v[226:227], v254 offset:0x1600
	ds_read_b64_tr_b16 v[228:229], v254 offset:0x1e00
	s_setprio 2
	v_exp_f32_e32 v64, v64
	v_exp_f32_e32 v65, v65
	v_exp_f32_e32 v66, v66
	v_exp_f32_e32 v67, v67
	v_exp_f32_e32 v68, v68
	v_exp_f32_e32 v69, v69
	v_add_f32_e32 v230, v65, v64
	v_exp_f32_e32 v70, v70
	v_add_f32_e32 v230, v66, v230
	v_exp_f32_e32 v71, v71
	v_add_f32_e32 v230, v67, v230
	v_exp_f32_e32 v72, v72
	v_add_f32_e32 v230, v68, v230
	v_exp_f32_e32 v73, v73
	v_add_f32_e32 v230, v69, v230
	v_exp_f32_e32 v74, v74
	v_add_f32_e32 v230, v70, v230
	v_exp_f32_e32 v75, v75
	v_add_f32_e32 v230, v71, v230
	v_exp_f32_e32 v76, v76
	v_add_f32_e32 v230, v72, v230
	v_exp_f32_e32 v77, v77
	v_add_f32_e32 v230, v73, v230
	v_exp_f32_e32 v78, v78
	v_add_f32_e32 v230, v74, v230
	v_exp_f32_e32 v79, v79
	v_add_f32_e32 v230, v75, v230
	v_add_f32_e32 v230, v76, v230
	v_add_f32_e32 v230, v77, v230
	v_add_f32_e32 v230, v78, v230
	v_add_f32_e32 v230, v79, v230
	v_add_f32_e32 v173, v173, v230
	v_cvt_pk_bf16_f32 v64, v64, v65
	v_cvt_pk_bf16_f32 v65, v66, v67
	v_cvt_pk_bf16_f32 v66, v68, v69
	v_cvt_pk_bf16_f32 v67, v70, v71
	v_cvt_pk_bf16_f32 v68, v72, v73
	v_cvt_pk_bf16_f32 v69, v74, v75
	v_cvt_pk_bf16_f32 v70, v76, v77
	v_cvt_pk_bf16_f32 v71, v78, v79
	s_nop 0
	v_permlane32_swap_b32_e32 v64, v66
	v_permlane32_swap_b32_e32 v65, v67
	v_permlane32_swap_b32_e32 v68, v70
	v_permlane32_swap_b32_e32 v69, v71
	s_waitcnt lgkmcnt(0)
	v_add_u32_e32 v72, v246, v151
	v_add_u32_e32 v73, v246, v149
	v_add_u32_e32 v74, v246, v148
	v_add_u32_e32 v75, v246, v147
	ds_read_b128 v[230:233], v74 offset:12416
	ds_read_b128 v[234:237], v75 offset:12416
	ds_read_b128 v[238:241], v72 offset:12544
	ds_read_b128 v[242:245], v73 offset:12544
	ds_read_b128 v[246:249], v74 offset:12544
	ds_read_b128 v[250:253], v75 offset:12544
	s_setprio 1
	v_mfma_f32_32x32x16_bf16 v[48:63], v[64:67], v[198:201], v[48:63]
	v_mfma_f32_32x32x16_bf16 v[32:47], v[64:67], v[206:209], v[32:47]
	v_mfma_f32_32x32x16_bf16 v[16:31], v[64:67], v[214:217], v[16:31]
	v_mfma_f32_32x32x16_bf16 v[0:15], v[64:67], v[222:225], v[0:15]
	v_mfma_f32_32x32x16_bf16 v[48:63], v[68:71], v[202:205], v[48:63]
	v_mfma_f32_32x32x16_bf16 v[32:47], v[68:71], v[210:213], v[32:47]
	v_mfma_f32_32x32x16_bf16 v[16:31], v[68:71], v[218:221], v[16:31]
	v_mfma_f32_32x32x16_bf16 v[0:15], v[68:71], v[226:229], v[0:15]
	s_waitcnt lgkmcnt(0)
; #define SBAR() __builtin_amdgcn_sched_barrier(0)
; #define ATT_DMA_K(t) do { const bf16_t* kg_ = Kh + (size_t)(t) * 64 * LDK; LAS unsigned char* sb_ = lds + ((t) & 3) * KBUF; \
;     _Pragma("unroll") for (int i_ = 0; i_ < NKP; ++i_) __builtin_amdgcn_global_load_lds((const unsigned*)(kg_ + kgo[i_]), (LAS unsigned*)(sb_ + (wid + 8 * i_) * 1024), 16, 0, 0); } while (0)
; #define ATT_DMA_V(t, vs) do { const bf16_t* vg_ = Vh + (size_t)(t) * 64 * LDV; LAS unsigned char* sb_ = lds + V_OFF + (vs) * SHM_V; \
;     _Pragma("unroll") for (int i_ = 0; i_ < 2; ++i_) __builtin_amdgcn_global_load_lds((const unsigned*)(vg_ + vgo[i_]), (LAS unsigned*)(sb_ + (2 * wid + i_) * 1024), 16, 0, 0); } while (0)
; #define ATT_SEG(t) do { if constexpr (MODE != 0) { if (((t) == tL && tL > 0) || (t) == tR) { const float f_ = (t) == tR ? fR : fL; l_reg *= f_; \
;     _Pragma("unroll") for (int d = 0; d < 4; ++d) _Pragma("unroll") for (int r = 0; r < 16; ++r) o[d][r] *= f_; } } } while (0)
; #define ATT_TOP(N) do { asm volatile("s_waitcnt vmcnt(%0)" :: "n"(N) : "memory"); __builtin_amdgcn_s_barrier(); asm volatile("" ::: "memory"); } while (0)
; template <int DQK, int MODE, int LDQ, int LDK, int LDV> ...
;     ...
;     for (int j = 0; j < NT; ++j) {
;         if (j + 2 < NT) ATT_TOP(NKP + 2); else ATT_TOP(0);
;         if (j + 3 < NT) ATT_DMA_K(j + 3);
;         if (j + 2 < NT) ATT_DMA_V(j + 2, v2);
;         ATT_SEG(j); SBAR();
;         ATT_STEP(pA, pB, 0, v0, true, 1, j);
;         ATT_STEP(pB, pA, 1, v0, (j + 1 < NT), 0, j + 1);
	v_mfma_f32_32x32x16_bf16 v[64:79], v[174:177], v[80:83], 0
	v_mfma_f32_32x32x16_bf16 v[64:79], v[178:181], v[84:87], v[64:79]
	v_mfma_f32_32x32x16_bf16 v[64:79], v[182:185], v[88:91], v[64:79]
	v_mfma_f32_32x32x16_bf16 v[64:79], v[186:189], v[92:95], v[64:79]
	v_mfma_f32_32x32x16_bf16 v[64:79], v[190:193], v[96:99], v[64:79]
	v_mfma_f32_32x32x16_bf16 v[64:79], v[194:197], v[100:103], v[64:79]
	v_mfma_f32_32x32x16_bf16 v[64:79], v[230:233], v[104:107], v[64:79]
	v_mfma_f32_32x32x16_bf16 v[64:79], v[234:237], v[108:111], v[64:79]
	v_mfma_f32_32x32x16_bf16 v[64:79], v[238:241], v[112:115], v[64:79]
	v_mfma_f32_32x32x16_bf16 v[64:79], v[242:245], v[116:119], v[64:79]
	v_mfma_f32_32x32x16_bf16 v[64:79], v[246:249], v[120:123], v[64:79]
	v_mfma_f32_32x32x16_bf16 v[64:79], v[250:253], v[124:127], v[64:79]
	s_setprio 0
	s_add_i32 s4, s43, -2
	s_and_b32 s4, s4, 3
	s_mulk_i32 s4, 0x6000
	v_add_u32_e32 v246, s4, v158
	v_add_u32_e32 v174, v246, v151
	v_add_u32_e32 v178, v246, v149
	v_add_u32_e32 v182, v246, v148
	v_add_u32_e32 v186, v246, v147
	ds_read_b128 v[190:193], v174 offset:128
	ds_read_b128 v[194:197], v178 offset:128
	ds_read_b128 v[174:177], v174
	ds_read_b128 v[178:181], v178
	ds_read_b128 v[182:185], v182
	ds_read_b128 v[186:189], v186
	ds_read_b64_tr_b16 v[198:199], v254 offset:0x2000
	ds_read_b64_tr_b16 v[200:201], v254 offset:0x2800
	ds_read_b64_tr_b16 v[202:203], v254 offset:0x3000
	ds_read_b64_tr_b16 v[204:205], v254 offset:0x3800
	ds_read_b64_tr_b16 v[206:207], v254 offset:0x2200
	ds_read_b64_tr_b16 v[208:209], v254 offset:0x2a00
	ds_read_b64_tr_b16 v[210:211], v254 offset:0x3200
	ds_read_b64_tr_b16 v[212:213], v254 offset:0x3a00
	ds_read_b64_tr_b16 v[214:215], v254 offset:0x2400
	ds_read_b64_tr_b16 v[216:217], v254 offset:0x2c00
	ds_read_b64_tr_b16 v[218:219], v254 offset:0x3400
	ds_read_b64_tr_b16 v[220:221], v254 offset:0x3c00
	ds_read_b64_tr_b16 v[222:223], v254 offset:0x2600
	ds_read_b64_tr_b16 v[224:225], v254 offset:0x2e00
	ds_read_b64_tr_b16 v[226:227], v254 offset:0x3600
	ds_read_b64_tr_b16 v[228:229], v254 offset:0x3e00
	s_setprio 2
	v_exp_f32_e32 v64, v64
	v_exp_f32_e32 v65, v65
	v_exp_f32_e32 v66, v66
	v_exp_f32_e32 v67, v67
	v_exp_f32_e32 v68, v68
	v_exp_f32_e32 v69, v69
	v_add_f32_e32 v230, v65, v64
	v_exp_f32_e32 v70, v70
	v_add_f32_e32 v230, v66, v230
	v_exp_f32_e32 v71, v71
	v_add_f32_e32 v230, v67, v230
	v_exp_f32_e32 v72, v72
	v_add_f32_e32 v230, v68, v230
	v_exp_f32_e32 v73, v73
	v_add_f32_e32 v230, v69, v230
	v_exp_f32_e32 v74, v74
	v_add_f32_e32 v230, v70, v230
	v_exp_f32_e32 v75, v75
	v_add_f32_e32 v230, v71, v230
	v_exp_f32_e32 v76, v76
	v_add_f32_e32 v230, v72, v230
	v_exp_f32_e32 v77, v77
	v_add_f32_e32 v230, v73, v230
	v_exp_f32_e32 v78, v78
	v_add_f32_e32 v230, v74, v230
	v_exp_f32_e32 v79, v79
	v_add_f32_e32 v230, v75, v230
	v_add_f32_e32 v230, v76, v230
	v_add_f32_e32 v230, v77, v230
	v_add_f32_e32 v230, v78, v230
	v_add_f32_e32 v230, v79, v230
	v_add_f32_e32 v173, v173, v230
	v_cvt_pk_bf16_f32 v64, v64, v65
	v_cvt_pk_bf16_f32 v65, v66, v67
	v_cvt_pk_bf16_f32 v66, v68, v69
	v_cvt_pk_bf16_f32 v67, v70, v71
	v_cvt_pk_bf16_f32 v68, v72, v73
	v_cvt_pk_bf16_f32 v69, v74, v75
	v_cvt_pk_bf16_f32 v70, v76, v77
	v_cvt_pk_bf16_f32 v71, v78, v79
	s_nop 0
	v_permlane32_swap_b32_e32 v64, v66
	v_permlane32_swap_b32_e32 v65, v67
	v_permlane32_swap_b32_e32 v68, v70
	v_permlane32_swap_b32_e32 v69, v71
	s_waitcnt lgkmcnt(0)
	v_add_u32_e32 v72, v246, v151
	v_add_u32_e32 v73, v246, v149
	v_add_u32_e32 v74, v246, v148
	v_add_u32_e32 v75, v246, v147
	ds_read_b128 v[230:233], v74 offset:128
	ds_read_b128 v[234:237], v75 offset:128
	ds_read_b128 v[238:241], v72 offset:256
	ds_read_b128 v[242:245], v73 offset:256
	ds_read_b128 v[246:249], v74 offset:256
	ds_read_b128 v[250:253], v75 offset:256
	s_setprio 1
	s_cmp_lt_u32 s33, 0x100
	s_cbranch_scc1 .Lstg_mla_mid_3
	s_waitcnt vmcnt(5)
	s_barrier
